# v36 + nt on the PEER table build's f32 source-row loads
# baseline (speedup 1.0000x reference)
; __device__ void phase_ffn_norm(const Params& p) {
;     ...
;   for (int r = gw; r < 2 * 16384; r += nw) {
;     const float* src = (r < 16384) ? p.in[22] + (size_t)r * DM : p.in[23] + (size_t)(r - 16384) * DM;
;     f32x4 v[4]; float am = 0.f;
; #pragma unroll
;     for (int i = 0; i < 4; ++i) { v[i] = *(const f32x4*)(src + lane * 16 + i * 4); am = fmaxf(am, fmaxf(fmaxf(fabsf(v[i][0]), fabsf(v[i][1])), fmaxf(fabsf(v[i][2]), fabsf(v[i][3])))); }
; #pragma unroll
;     for (int o = 32; o >= 1; o >>= 1) am = fmaxf(am, __shfl_xor(am, o));
;     const float sc = am > 0.f ? 224.f / am : 1.f;
;     u32x4 w;
; #pragma unroll
;     for (int i = 0; i < 4; ++i) {
;       int d = 0;
;       d = __builtin_amdgcn_cvt_pk_fp8_f32(v[i][0] * sc, v[i][1] * sc, d, false);
;       d = __builtin_amdgcn_cvt_pk_fp8_f32(v[i][2] * sc, v[i][3] * sc, d, true);
;       w[i] = (unsigned)d;
;     }
;     *(u32x4*)(q8 + (r < 16384 ? (size_t)r * 2048 : (size_t)(r - 16384) * 2048 + 1024) + lane * 16) = w;
;     if (lane == 0) qs[r] = am > 0.f ? am / 224.f : 1.f;
;   }
.Lcv_loop:
	s_and_b32 s41, s40, 0x3fff
	s_cmp_lt_u32 s40, 0x4000
	s_cselect_b32 s42, s10, s12
	s_cselect_b32 s43, s11, s13
	s_cselect_b32 s45, 0, 0x400
	s_lshl_b32 s44, s41, 12
	s_add_u32 s42, s42, s44
	s_addc_u32 s43, s43, 0
	s_lshl_b32 s44, s41, 11
	s_add_i32 s44, s44, s45
	s_add_u32 s46, s58, s44
	s_addc_u32 s47, s59, 0
	s_lshl_b32 s44, s40, 2
	s_add_u32 s48, s58, s44
	s_addc_u32 s49, s59, 0
	s_add_u32 s48, s48, 0x2000000
	s_addc_u32 s49, s49, 0
	global_load_dwordx4 v[16:19], v0, s[42:43] nt
	global_load_dwordx4 v[20:23], v0, s[42:43] offset:16 nt
	global_load_dwordx4 v[24:27], v0, s[42:43] offset:32 nt
	global_load_dwordx4 v[28:31], v0, s[42:43] offset:48 nt
	s_add_i32 s68, s40, 0x780
	s_cmp_lt_u32 s68, 0x8000
	s_cbranch_scc0 .Lcv_single
	s_and_b32 s41, s68, 0x3fff
	s_cmp_lt_u32 s68, 0x4000
	s_cselect_b32 s60, s10, s12
	s_cselect_b32 s61, s11, s13
	s_cselect_b32 s45, 0, 0x400
	s_lshl_b32 s44, s41, 12
	s_add_u32 s60, s60, s44
	s_addc_u32 s61, s61, 0
	s_lshl_b32 s44, s41, 11
	s_add_i32 s44, s44, s45
	s_add_u32 s62, s58, s44
	s_addc_u32 s63, s59, 0
	s_lshl_b32 s44, s68, 2
	s_add_u32 s64, s58, s44
	s_addc_u32 s65, s59, 0
	s_add_u32 s64, s64, 0x2000000
	s_addc_u32 s65, s65, 0
	global_load_dwordx4 v[32:35], v0, s[60:61] nt
	global_load_dwordx4 v[36:39], v0, s[60:61] offset:16 nt
	global_load_dwordx4 v[40:43], v0, s[60:61] offset:32 nt
	global_load_dwordx4 v[44:47], v0, s[60:61] offset:48 nt
	s_waitcnt vmcnt(4)
	v_mov_b32_e32 v10, 0
	v_max3_f32 v10, |v16|, |v17|, v10
	v_max3_f32 v10, |v18|, |v19|, v10
	v_max3_f32 v10, |v20|, |v21|, v10
	v_max3_f32 v10, |v22|, |v23|, v10
	v_max3_f32 v10, |v24|, |v25|, v10
	v_max3_f32 v10, |v26|, |v27|, v10
	v_max3_f32 v10, |v28|, |v29|, v10
	v_max3_f32 v10, |v30|, |v31|, v10
	ds_bpermute_b32 v11, v2, v10
	s_waitcnt lgkmcnt(0)
	v_max_f32_e32 v10, v10, v11
	ds_bpermute_b32 v11, v3, v10
	s_waitcnt lgkmcnt(0)
	v_max_f32_e32 v10, v10, v11
	ds_bpermute_b32 v11, v4, v10
	s_waitcnt lgkmcnt(0)
	v_max_f32_e32 v10, v10, v11
	ds_bpermute_b32 v11, v5, v10
	s_waitcnt lgkmcnt(0)
	v_max_f32_e32 v10, v10, v11
	ds_bpermute_b32 v11, v6, v10
	s_waitcnt lgkmcnt(0)
	v_max_f32_e32 v10, v10, v11
	ds_bpermute_b32 v11, v7, v10
	s_waitcnt lgkmcnt(0)
	v_max_f32_e32 v10, v10, v11
	v_div_scale_f32 v11, s[50:51], v10, v10, v8
	v_rcp_f32_e32 v12, v11
	v_div_scale_f32 v13, vcc, v8, v10, v8
	v_cmp_lt_f32_e64 s[70:71], 0, v10
	v_fma_f32 v14, -v11, v12, 1.0
	v_fmac_f32_e32 v12, v14, v12
	v_mul_f32_e32 v14, v13, v12
	v_fma_f32 v15, -v11, v14, v13
	v_fmac_f32_e32 v14, v15, v12
	v_fma_f32 v13, -v11, v14, v13
	v_div_fmas_f32 v13, v13, v12, v14
	v_div_fixup_f32 v13, v13, v10, v8
	v_cndmask_b32_e64 v13, 1.0, v13, s[70:71]
	v_mul_f32_e32 v16, v16, v13
	v_mul_f32_e32 v17, v17, v13
	v_mul_f32_e32 v18, v18, v13
	v_mul_f32_e32 v19, v19, v13
	v_mul_f32_e32 v20, v20, v13
	v_mul_f32_e32 v21, v21, v13
	v_mul_f32_e32 v22, v22, v13
	v_mul_f32_e32 v23, v23, v13
	v_mul_f32_e32 v24, v24, v13
	v_mul_f32_e32 v25, v25, v13
	v_mul_f32_e32 v26, v26, v13
	v_mul_f32_e32 v27, v27, v13
	v_mul_f32_e32 v28, v28, v13
	v_mul_f32_e32 v29, v29, v13
	v_mul_f32_e32 v30, v30, v13
	v_mul_f32_e32 v31, v31, v13
	v_mov_b32_e32 v48, 0
	v_mov_b32_e32 v49, 0
	v_mov_b32_e32 v50, 0
	v_mov_b32_e32 v51, 0
	v_cvt_pk_fp8_f32 v48, v16, v17
	v_cvt_pk_fp8_f32 v49, v20, v21
	v_cvt_pk_fp8_f32 v50, v24, v25
	v_cvt_pk_fp8_f32 v51, v28, v29
	v_cvt_pk_fp8_f32 v48, v18, v19 op_sel:[0,0,1]
	v_cvt_pk_fp8_f32 v49, v22, v23 op_sel:[0,0,1]
	v_cvt_pk_fp8_f32 v50, v26, v27 op_sel:[0,0,1]
	v_cvt_pk_fp8_f32 v51, v30, v31 op_sel:[0,0,1]
	v_div_scale_f32 v11, s[50:51], v8, v8, v10
	v_rcp_f32_e32 v12, v11
	v_div_scale_f32 v13, vcc, v10, v8, v10
	v_fma_f32 v14, -v11, v12, 1.0
	v_fmac_f32_e32 v12, v14, v12
	v_mul_f32_e32 v14, v13, v12
	v_fma_f32 v15, -v11, v14, v13
	v_fmac_f32_e32 v14, v15, v12
	v_fma_f32 v11, -v11, v14, v13
	v_div_fmas_f32 v11, v11, v12, v14
	v_div_fixup_f32 v11, v11, v8, v10
	v_cndmask_b32_e64 v11, 1.0, v11, s[70:71]
	global_store_dwordx4 v1, v[48:51], s[46:47]
	s_mov_b64 exec, 1
	global_store_dword v9, v11, s[48:49]
	s_mov_b64 exec, -1
	s_waitcnt vmcnt(2)
	v_mov_b32_e32 v10, 0
	v_max3_f32 v10, |v32|, |v33|, v10
	v_max3_f32 v10, |v34|, |v35|, v10
	v_max3_f32 v10, |v36|, |v37|, v10
	v_max3_f32 v10, |v38|, |v39|, v10
	v_max3_f32 v10, |v40|, |v41|, v10
	v_max3_f32 v10, |v42|, |v43|, v10
	v_max3_f32 v10, |v44|, |v45|, v10
	v_max3_f32 v10, |v46|, |v47|, v10
	ds_bpermute_b32 v11, v2, v10
	s_waitcnt lgkmcnt(0)
	v_max_f32_e32 v10, v10, v11
	ds_bpermute_b32 v11, v3, v10
	s_waitcnt lgkmcnt(0)
	v_max_f32_e32 v10, v10, v11
	ds_bpermute_b32 v11, v4, v10
	s_waitcnt lgkmcnt(0)
	v_max_f32_e32 v10, v10, v11
	ds_bpermute_b32 v11, v5, v10
	s_waitcnt lgkmcnt(0)
	v_max_f32_e32 v10, v10, v11
	ds_bpermute_b32 v11, v6, v10
	s_waitcnt lgkmcnt(0)
	v_max_f32_e32 v10, v10, v11
	ds_bpermute_b32 v11, v7, v10
	s_waitcnt lgkmcnt(0)
	v_max_f32_e32 v10, v10, v11
	v_div_scale_f32 v11, s[50:51], v10, v10, v8
	v_rcp_f32_e32 v12, v11
	v_div_scale_f32 v13, vcc, v8, v10, v8
	v_cmp_lt_f32_e64 s[70:71], 0, v10
	v_fma_f32 v14, -v11, v12, 1.0
	v_fmac_f32_e32 v12, v14, v12
	v_mul_f32_e32 v14, v13, v12
	v_fma_f32 v15, -v11, v14, v13
	v_fmac_f32_e32 v14, v15, v12
	v_fma_f32 v13, -v11, v14, v13
	v_div_fmas_f32 v13, v13, v12, v14
	v_div_fixup_f32 v13, v13, v10, v8
	v_cndmask_b32_e64 v13, 1.0, v13, s[70:71]
	v_mul_f32_e32 v32, v32, v13
	v_mul_f32_e32 v33, v33, v13
	v_mul_f32_e32 v34, v34, v13
	v_mul_f32_e32 v35, v35, v13
	v_mul_f32_e32 v36, v36, v13
	v_mul_f32_e32 v37, v37, v13
	v_mul_f32_e32 v38, v38, v13
	v_mul_f32_e32 v39, v39, v13
	v_mul_f32_e32 v40, v40, v13
	v_mul_f32_e32 v41, v41, v13
	v_mul_f32_e32 v42, v42, v13
	v_mul_f32_e32 v43, v43, v13
	v_mul_f32_e32 v44, v44, v13
	v_mul_f32_e32 v45, v45, v13
	v_mul_f32_e32 v46, v46, v13
	v_mul_f32_e32 v47, v47, v13
	v_mov_b32_e32 v48, 0
	v_mov_b32_e32 v49, 0
	v_mov_b32_e32 v50, 0
	v_mov_b32_e32 v51, 0
	v_cvt_pk_fp8_f32 v48, v32, v33
	v_cvt_pk_fp8_f32 v49, v36, v37
	v_cvt_pk_fp8_f32 v50, v40, v41
	v_cvt_pk_fp8_f32 v51, v44, v45
	v_cvt_pk_fp8_f32 v48, v34, v35 op_sel:[0,0,1]
	v_cvt_pk_fp8_f32 v49, v38, v39 op_sel:[0,0,1]
	v_cvt_pk_fp8_f32 v50, v42, v43 op_sel:[0,0,1]
	v_cvt_pk_fp8_f32 v51, v46, v47 op_sel:[0,0,1]
	v_div_scale_f32 v11, s[50:51], v8, v8, v10
	v_rcp_f32_e32 v12, v11
	v_div_scale_f32 v13, vcc, v10, v8, v10
	v_fma_f32 v14, -v11, v12, 1.0
	v_fmac_f32_e32 v12, v14, v12
	v_mul_f32_e32 v14, v13, v12
	v_fma_f32 v15, -v11, v14, v13
	v_fmac_f32_e32 v14, v15, v12
	v_fma_f32 v11, -v11, v14, v13
	v_div_fmas_f32 v11, v11, v12, v14
	v_div_fixup_f32 v11, v11, v8, v10
	v_cndmask_b32_e64 v11, 1.0, v11, s[70:71]
	global_store_dwordx4 v1, v[48:51], s[62:63]
	s_mov_b64 exec, 1
	global_store_dword v9, v11, s[64:65]
	s_mov_b64 exec, -1
	s_add_i32 s40, s40, 0xf00
	s_cmp_lt_u32 s40, 0x8000
	s_cbranch_scc1 .Lcv_loop
	s_branch .Lcv_done
